# in-proj GEMM K loop: counted lgkmcnt waits inside the MFMA clusters instead of lgkmcnt(0) before each cluster
# speedup vs baseline: 1.0024x; 1.0024x over previous
.LBB0_189:
	s_add_u32 s1, s68, 0xfff80080
	s_addc_u32 s2, s69, -1
	s_add_i32 s3, 0, 0x10000
	v_add_u32_e32 v154, s3, v143
	ds_read_b128 v[138:141], v154
	ds_read_b128 v[146:149], v154 offset:1024
	ds_read_b128 v[150:153], v154 offset:2048
	ds_read_b128 v[154:157], v154 offset:3072
	s_cmp_eq_u32 s87, 28
	s_cselect_b32 s73, s43, s2
	s_cselect_b32 s72, s81, s1
	s_cselect_b32 s71, s41, s86
	s_cselect_b32 s70, s82, s83
	v_lshl_add_u64 v[174:175], s[68:69], 0, v[134:135]
	s_add_i32 m0, s60, 0xc000
	ds_read_b128 v[158:161], v145
	ds_read_b128 v[162:165], v145 offset:1024
	ds_read_b128 v[166:169], v145 offset:2048
	ds_read_b128 v[170:173], v145 offset:3072
	ds_read_b128 v[182:185], v145 offset:4096
	ds_read_b128 v[206:209], v145 offset:5120
	ds_read_b128 v[210:213], v145 offset:6144
	ds_read_b128 v[214:217], v145 offset:7168
	global_load_lds_dwordx4 v[174:175], off
	v_lshl_add_u64 v[174:175], s[68:69], 0, v[136:137]
	s_add_i32 m0, s60, 0xe000
	s_nop 0
	global_load_lds_dwordx4 v[174:175], off
	s_waitcnt lgkmcnt(8)
	s_barrier
	s_waitcnt lgkmcnt(7)
	s_setprio 1
	s_waitcnt lgkmcnt(7)
	v_mfma_f32_16x16x32_bf16 v[124:127], v[138:141], v[158:161], v[124:127]
	v_mfma_f32_16x16x32_bf16 v[120:123], v[150:153], v[158:161], v[120:123]
	s_waitcnt lgkmcnt(5)
	v_mfma_f32_16x16x32_bf16 v[116:119], v[138:141], v[166:169], v[116:119]
	v_mfma_f32_16x16x32_bf16 v[108:111], v[150:153], v[166:169], v[108:111]
	s_waitcnt lgkmcnt(3)
	v_mfma_f32_16x16x32_bf16 v[100:103], v[138:141], v[182:185], v[100:103]
	v_mfma_f32_16x16x32_bf16 v[92:95], v[150:153], v[182:185], v[92:95]
	s_waitcnt lgkmcnt(1)
	v_mfma_f32_16x16x32_bf16 v[84:87], v[138:141], v[210:213], v[84:87]
	v_mfma_f32_16x16x32_bf16 v[76:79], v[150:153], v[210:213], v[76:79]
	v_mfma_f32_16x16x32_bf16 v[124:127], v[146:149], v[162:165], v[124:127]
	v_mfma_f32_16x16x32_bf16 v[120:123], v[154:157], v[162:165], v[120:123]
	v_mfma_f32_16x16x32_bf16 v[116:119], v[146:149], v[170:173], v[116:119]
	v_mfma_f32_16x16x32_bf16 v[108:111], v[154:157], v[170:173], v[108:111]
	v_mfma_f32_16x16x32_bf16 v[100:103], v[146:149], v[206:209], v[100:103]
	v_mfma_f32_16x16x32_bf16 v[92:95], v[154:157], v[206:209], v[92:95]
	s_waitcnt lgkmcnt(0)
	v_mfma_f32_16x16x32_bf16 v[84:87], v[146:149], v[214:217], v[84:87]
	v_mfma_f32_16x16x32_bf16 v[76:79], v[154:157], v[214:217], v[76:79]
	s_setprio 0
	s_barrier
	s_add_i32 s1, 0, 0x14000
	v_add_u32_e32 v174, s1, v143
	s_add_i32 s2, s3, s53
	ds_read_b128 v[218:221], v174
	ds_read_b128 v[222:225], v174 offset:1024
	ds_read_b128 v[226:229], v174 offset:2048
	ds_read_b128 v[230:233], v174 offset:3072
	v_lshl_add_u64 v[174:175], s[70:71], 0, v[176:177]
	s_mov_b32 m0, s2
	v_lshl_add_u64 v[186:187], s[70:71], 0, v[128:129]
	global_load_lds_dwordx4 v[174:175], off
	s_add_i32 m0, s2, 0x2000
	s_nop 0
	global_load_lds_dwordx4 v[186:187], off
	s_barrier
	s_waitcnt lgkmcnt(3)
	s_setprio 1
	s_waitcnt lgkmcnt(3)
	v_mfma_f32_16x16x32_bf16 v[112:115], v[218:221], v[158:161], v[112:115]
	s_waitcnt lgkmcnt(1)
	v_mfma_f32_16x16x32_bf16 v[104:107], v[226:229], v[158:161], v[104:107]
	v_mfma_f32_16x16x32_bf16 v[96:99], v[218:221], v[166:169], v[96:99]
	v_mfma_f32_16x16x32_bf16 v[88:91], v[226:229], v[166:169], v[88:91]
	v_mfma_f32_16x16x32_bf16 v[80:83], v[218:221], v[182:185], v[80:83]
	v_mfma_f32_16x16x32_bf16 v[72:75], v[226:229], v[182:185], v[72:75]
	v_mfma_f32_16x16x32_bf16 v[68:71], v[218:221], v[210:213], v[68:71]
	v_mfma_f32_16x16x32_bf16 v[64:67], v[226:229], v[210:213], v[64:67]
	v_mfma_f32_16x16x32_bf16 v[112:115], v[222:225], v[162:165], v[112:115]
	s_waitcnt lgkmcnt(0)
	v_mfma_f32_16x16x32_bf16 v[104:107], v[230:233], v[162:165], v[104:107]
	v_mfma_f32_16x16x32_bf16 v[96:99], v[222:225], v[170:173], v[96:99]
	v_mfma_f32_16x16x32_bf16 v[88:91], v[230:233], v[170:173], v[88:91]
	v_mfma_f32_16x16x32_bf16 v[80:83], v[222:225], v[206:209], v[80:83]
	v_mfma_f32_16x16x32_bf16 v[72:75], v[230:233], v[206:209], v[72:75]
	v_mfma_f32_16x16x32_bf16 v[68:71], v[222:225], v[214:217], v[68:71]
	v_mfma_f32_16x16x32_bf16 v[64:67], v[230:233], v[214:217], v[64:67]
	s_setprio 0
	s_mov_b32 m0, s60
	v_lshl_add_u64 v[200:201], s[72:73], 0, v[132:133]
	s_barrier
	ds_read_b128 v[158:161], v145 offset:16384
	ds_read_b128 v[162:165], v145 offset:17408
	ds_read_b128 v[166:169], v145 offset:18432
	ds_read_b128 v[170:173], v145 offset:19456
	ds_read_b128 v[182:185], v145 offset:20480
	ds_read_b128 v[206:209], v145 offset:21504
	ds_read_b128 v[210:213], v145 offset:22528
	ds_read_b128 v[214:217], v145 offset:23552
	global_load_lds_dwordx4 v[200:201], off
	v_lshl_add_u64 v[202:203], s[72:73], 0, v[130:131]
	s_mov_b32 m0, s61
	s_nop 0
	global_load_lds_dwordx4 v[202:203], off
	s_barrier
	s_waitcnt lgkmcnt(7)
	s_setprio 1
	s_waitcnt lgkmcnt(7)
	v_mfma_f32_16x16x32_bf16 v[60:63], v[138:141], v[158:161], v[60:63]
	v_mfma_f32_16x16x32_bf16 v[56:59], v[150:153], v[158:161], v[56:59]
	s_waitcnt lgkmcnt(5)
	v_mfma_f32_16x16x32_bf16 v[52:55], v[138:141], v[166:169], v[52:55]
	v_mfma_f32_16x16x32_bf16 v[44:47], v[150:153], v[166:169], v[44:47]
	s_waitcnt lgkmcnt(3)
	v_mfma_f32_16x16x32_bf16 v[36:39], v[138:141], v[182:185], v[36:39]
	v_mfma_f32_16x16x32_bf16 v[28:31], v[150:153], v[182:185], v[28:31]
	s_waitcnt lgkmcnt(1)
	v_mfma_f32_16x16x32_bf16 v[20:23], v[138:141], v[210:213], v[20:23]
	v_mfma_f32_16x16x32_bf16 v[12:15], v[150:153], v[210:213], v[12:15]
	v_mfma_f32_16x16x32_bf16 v[60:63], v[146:149], v[162:165], v[60:63]
	v_mfma_f32_16x16x32_bf16 v[56:59], v[154:157], v[162:165], v[56:59]
	v_mfma_f32_16x16x32_bf16 v[52:55], v[146:149], v[170:173], v[52:55]
	v_mfma_f32_16x16x32_bf16 v[44:47], v[154:157], v[170:173], v[44:47]
	v_mfma_f32_16x16x32_bf16 v[36:39], v[146:149], v[206:209], v[36:39]
	v_mfma_f32_16x16x32_bf16 v[28:31], v[154:157], v[206:209], v[28:31]
	s_waitcnt lgkmcnt(0)
	v_mfma_f32_16x16x32_bf16 v[20:23], v[146:149], v[214:217], v[20:23]
	v_mfma_f32_16x16x32_bf16 v[12:15], v[154:157], v[214:217], v[12:15]
	s_setprio 0
	s_barrier
	s_add_u32 s2, s70, 0x80000
	s_addc_u32 s3, s71, 0
	s_add_i32 s1, s1, s53
	v_lshl_add_u64 v[138:139], s[2:3], 0, v[176:177]
	s_mov_b32 m0, s1
	s_nop 0
	global_load_lds_dwordx4 v[138:139], off
	v_lshl_add_u64 v[138:139], s[2:3], 0, v[128:129]
	s_add_i32 m0, s1, 0x2000
	s_nop 0
	global_load_lds_dwordx4 v[138:139], off
	s_waitcnt vmcnt(6)
	s_barrier
	s_setprio 1
	v_mfma_f32_16x16x32_bf16 v[48:51], v[218:221], v[158:161], v[48:51]
	v_mfma_f32_16x16x32_bf16 v[40:43], v[226:229], v[158:161], v[40:43]
	v_mfma_f32_16x16x32_bf16 v[32:35], v[218:221], v[166:169], v[32:35]
	v_mfma_f32_16x16x32_bf16 v[24:27], v[226:229], v[166:169], v[24:27]
	v_mfma_f32_16x16x32_bf16 v[16:19], v[218:221], v[182:185], v[16:19]
	v_mfma_f32_16x16x32_bf16 v[8:11], v[226:229], v[182:185], v[8:11]
	v_mfma_f32_16x16x32_bf16 v[4:7], v[218:221], v[210:213], v[4:7]
	v_mfma_f32_16x16x32_bf16 v[0:3], v[226:229], v[210:213], v[0:3]
	v_mfma_f32_16x16x32_bf16 v[48:51], v[222:225], v[162:165], v[48:51]
	v_mfma_f32_16x16x32_bf16 v[40:43], v[230:233], v[162:165], v[40:43]
	v_mfma_f32_16x16x32_bf16 v[32:35], v[222:225], v[170:173], v[32:35]
	v_mfma_f32_16x16x32_bf16 v[24:27], v[230:233], v[170:173], v[24:27]
	v_mfma_f32_16x16x32_bf16 v[16:19], v[222:225], v[206:209], v[16:19]
	v_mfma_f32_16x16x32_bf16 v[8:11], v[230:233], v[206:209], v[8:11]
	v_mfma_f32_16x16x32_bf16 v[4:7], v[222:225], v[214:217], v[4:7]
	v_mfma_f32_16x16x32_bf16 v[0:3], v[230:233], v[214:217], v[0:3]
	s_setprio 0
	s_add_i32 s1, 0, 0x18000
	v_add_u32_e32 v154, s1, v143
	s_barrier
	ds_read_b128 v[138:141], v154
	ds_read_b128 v[146:149], v154 offset:1024
	ds_read_b128 v[150:153], v154 offset:2048
	ds_read_b128 v[154:157], v154 offset:3072
	s_add_u32 s2, s72, 0x80000
	s_addc_u32 s3, s73, 0
	s_mov_b32 m0, s74
	v_lshl_add_u64 v[204:205], s[2:3], 0, v[132:133]
	ds_read_b128 v[158:161], v145 offset:32768
	ds_read_b128 v[162:165], v145 offset:33792
	ds_read_b128 v[166:169], v145 offset:34816
	ds_read_b128 v[170:173], v145 offset:35840
	ds_read_b128 v[182:185], v145 offset:36864
	ds_read_b128 v[206:209], v145 offset:37888
	ds_read_b128 v[210:213], v145 offset:38912
	ds_read_b128 v[214:217], v145 offset:39936
	global_load_lds_dwordx4 v[204:205], off
	v_lshl_add_u64 v[204:205], s[2:3], 0, v[130:131]
	s_mov_b32 m0, s75
	s_nop 0
	global_load_lds_dwordx4 v[204:205], off
	s_waitcnt lgkmcnt(8)
	s_barrier
	s_waitcnt lgkmcnt(7)
	s_setprio 1
	s_waitcnt lgkmcnt(7)
	v_mfma_f32_16x16x32_bf16 v[124:127], v[138:141], v[158:161], v[124:127]
	v_mfma_f32_16x16x32_bf16 v[120:123], v[150:153], v[158:161], v[120:123]
	s_waitcnt lgkmcnt(5)
	v_mfma_f32_16x16x32_bf16 v[116:119], v[138:141], v[166:169], v[116:119]
	v_mfma_f32_16x16x32_bf16 v[108:111], v[150:153], v[166:169], v[108:111]
	s_waitcnt lgkmcnt(3)
	v_mfma_f32_16x16x32_bf16 v[100:103], v[138:141], v[182:185], v[100:103]
	v_mfma_f32_16x16x32_bf16 v[92:95], v[150:153], v[182:185], v[92:95]
	s_waitcnt lgkmcnt(1)
	v_mfma_f32_16x16x32_bf16 v[84:87], v[138:141], v[210:213], v[84:87]
	v_mfma_f32_16x16x32_bf16 v[76:79], v[150:153], v[210:213], v[76:79]
	v_mfma_f32_16x16x32_bf16 v[124:127], v[146:149], v[162:165], v[124:127]
	v_mfma_f32_16x16x32_bf16 v[120:123], v[154:157], v[162:165], v[120:123]
	v_mfma_f32_16x16x32_bf16 v[116:119], v[146:149], v[170:173], v[116:119]
	v_mfma_f32_16x16x32_bf16 v[108:111], v[154:157], v[170:173], v[108:111]
	v_mfma_f32_16x16x32_bf16 v[100:103], v[146:149], v[206:209], v[100:103]
	v_mfma_f32_16x16x32_bf16 v[92:95], v[154:157], v[206:209], v[92:95]
	s_waitcnt lgkmcnt(0)
	v_mfma_f32_16x16x32_bf16 v[84:87], v[146:149], v[214:217], v[84:87]
	v_mfma_f32_16x16x32_bf16 v[76:79], v[154:157], v[214:217], v[76:79]
	s_setprio 0
	s_barrier
	s_add_i32 s12, 0, 0x1c000
	s_add_i32 s1, s1, s53
	v_add_u32_e32 v188, s12, v143
	v_lshl_add_u64 v[174:175], v[174:175], 0, s[20:21]
	s_mov_b32 m0, s1
	ds_read_b128 v[218:221], v188
	ds_read_b128 v[222:225], v188 offset:1024
	ds_read_b128 v[226:229], v188 offset:2048
	ds_read_b128 v[230:233], v188 offset:3072
	global_load_lds_dwordx4 v[174:175], off
	v_lshl_add_u64 v[174:175], v[186:187], 0, s[20:21]
	s_add_i32 m0, s1, 0x2000
	s_nop 0
	global_load_lds_dwordx4 v[174:175], off
	s_barrier
	s_waitcnt lgkmcnt(3)
	s_setprio 1
	s_waitcnt lgkmcnt(3)
	v_mfma_f32_16x16x32_bf16 v[112:115], v[218:221], v[158:161], v[112:115]
	s_waitcnt lgkmcnt(1)
	v_mfma_f32_16x16x32_bf16 v[104:107], v[226:229], v[158:161], v[104:107]
	v_mfma_f32_16x16x32_bf16 v[96:99], v[218:221], v[166:169], v[96:99]
	v_mfma_f32_16x16x32_bf16 v[88:91], v[226:229], v[166:169], v[88:91]
	v_mfma_f32_16x16x32_bf16 v[80:83], v[218:221], v[182:185], v[80:83]
	v_mfma_f32_16x16x32_bf16 v[72:75], v[226:229], v[182:185], v[72:75]
	v_mfma_f32_16x16x32_bf16 v[68:71], v[218:221], v[210:213], v[68:71]
	v_mfma_f32_16x16x32_bf16 v[64:67], v[226:229], v[210:213], v[64:67]
	v_mfma_f32_16x16x32_bf16 v[112:115], v[222:225], v[162:165], v[112:115]
	s_waitcnt lgkmcnt(0)
	v_mfma_f32_16x16x32_bf16 v[104:107], v[230:233], v[162:165], v[104:107]
	v_mfma_f32_16x16x32_bf16 v[96:99], v[222:225], v[170:173], v[96:99]
	v_mfma_f32_16x16x32_bf16 v[88:91], v[230:233], v[170:173], v[88:91]
	v_mfma_f32_16x16x32_bf16 v[80:83], v[222:225], v[206:209], v[80:83]
	v_mfma_f32_16x16x32_bf16 v[72:75], v[230:233], v[206:209], v[72:75]
	v_mfma_f32_16x16x32_bf16 v[68:71], v[222:225], v[214:217], v[68:71]
	v_mfma_f32_16x16x32_bf16 v[64:67], v[230:233], v[214:217], v[64:67]
	s_setprio 0
	s_mov_b32 m0, s76
	v_lshl_add_u64 v[174:175], v[200:201], 0, s[20:21]
	s_barrier
	ds_read_b128 v[158:161], v145 offset:49152
	ds_read_b128 v[162:165], v145 offset:50176
	ds_read_b128 v[166:169], v145 offset:51200
	ds_read_b128 v[170:173], v145 offset:52224
	ds_read_b128 v[182:185], v145 offset:53248
	ds_read_b128 v[206:209], v145 offset:54272
	ds_read_b128 v[210:213], v145 offset:55296
	ds_read_b128 v[214:217], v145 offset:56320
	global_load_lds_dwordx4 v[174:175], off
	v_lshl_add_u64 v[174:175], v[202:203], 0, s[20:21]
	s_mov_b32 m0, s77
	s_nop 0
	global_load_lds_dwordx4 v[174:175], off
	s_barrier
	s_waitcnt lgkmcnt(7)
	s_setprio 1
	s_waitcnt lgkmcnt(7)
	v_mfma_f32_16x16x32_bf16 v[60:63], v[138:141], v[158:161], v[60:63]
	v_mfma_f32_16x16x32_bf16 v[56:59], v[150:153], v[158:161], v[56:59]
	s_waitcnt lgkmcnt(5)
	v_mfma_f32_16x16x32_bf16 v[52:55], v[138:141], v[166:169], v[52:55]
	v_mfma_f32_16x16x32_bf16 v[44:47], v[150:153], v[166:169], v[44:47]
	s_waitcnt lgkmcnt(3)
	v_mfma_f32_16x16x32_bf16 v[36:39], v[138:141], v[182:185], v[36:39]
	v_mfma_f32_16x16x32_bf16 v[28:31], v[150:153], v[182:185], v[28:31]
	s_waitcnt lgkmcnt(1)
	v_mfma_f32_16x16x32_bf16 v[20:23], v[138:141], v[210:213], v[20:23]
	v_mfma_f32_16x16x32_bf16 v[12:15], v[150:153], v[210:213], v[12:15]
	v_mfma_f32_16x16x32_bf16 v[60:63], v[146:149], v[162:165], v[60:63]
	v_mfma_f32_16x16x32_bf16 v[56:59], v[154:157], v[162:165], v[56:59]
	v_mfma_f32_16x16x32_bf16 v[52:55], v[146:149], v[170:173], v[52:55]
	v_mfma_f32_16x16x32_bf16 v[44:47], v[154:157], v[170:173], v[44:47]
	v_mfma_f32_16x16x32_bf16 v[36:39], v[146:149], v[206:209], v[36:39]
	v_mfma_f32_16x16x32_bf16 v[28:31], v[154:157], v[206:209], v[28:31]
	s_waitcnt lgkmcnt(0)
	v_mfma_f32_16x16x32_bf16 v[20:23], v[146:149], v[214:217], v[20:23]
	v_mfma_f32_16x16x32_bf16 v[12:15], v[154:157], v[214:217], v[12:15]
	s_setprio 0
	s_barrier
	s_add_u32 s2, s70, 0x80080
	s_addc_u32 s3, s71, 0
	s_add_i32 s1, s12, s53
	v_lshl_add_u64 v[138:139], s[2:3], 0, v[176:177]
	s_mov_b32 m0, s1
	s_nop 0
	global_load_lds_dwordx4 v[138:139], off
	v_lshl_add_u64 v[138:139], s[2:3], 0, v[128:129]
	s_add_i32 m0, s1, 0x2000
	s_nop 0
	global_load_lds_dwordx4 v[138:139], off
	s_waitcnt vmcnt(6)
	s_barrier
	s_setprio 1
	v_mfma_f32_16x16x32_bf16 v[48:51], v[218:221], v[158:161], v[48:51]
	v_mfma_f32_16x16x32_bf16 v[40:43], v[226:229], v[158:161], v[40:43]
	v_mfma_f32_16x16x32_bf16 v[32:35], v[218:221], v[166:169], v[32:35]
	v_mfma_f32_16x16x32_bf16 v[24:27], v[226:229], v[166:169], v[24:27]
	v_mfma_f32_16x16x32_bf16 v[16:19], v[218:221], v[182:185], v[16:19]
	v_mfma_f32_16x16x32_bf16 v[8:11], v[226:229], v[182:185], v[8:11]
	v_mfma_f32_16x16x32_bf16 v[4:7], v[218:221], v[210:213], v[4:7]
	v_mfma_f32_16x16x32_bf16 v[0:3], v[226:229], v[210:213], v[0:3]
	v_mfma_f32_16x16x32_bf16 v[48:51], v[222:225], v[162:165], v[48:51]
	v_mfma_f32_16x16x32_bf16 v[40:43], v[230:233], v[162:165], v[40:43]
	v_mfma_f32_16x16x32_bf16 v[32:35], v[222:225], v[170:173], v[32:35]
	v_mfma_f32_16x16x32_bf16 v[24:27], v[230:233], v[170:173], v[24:27]
	v_mfma_f32_16x16x32_bf16 v[16:19], v[222:225], v[206:209], v[16:19]
	v_mfma_f32_16x16x32_bf16 v[8:11], v[230:233], v[206:209], v[8:11]
	v_mfma_f32_16x16x32_bf16 v[4:7], v[222:225], v[214:217], v[4:7]
	v_mfma_f32_16x16x32_bf16 v[0:3], v[230:233], v[214:217], v[0:3]
	s_setprio 0
	s_add_i32 s87, s87, 2
	s_add_u32 s68, s68, 0x100
	s_addc_u32 s69, s69, 0
	s_add_u32 s83, s83, 0x100
	s_addc_u32 s86, s86, 0
	s_cmp_gt_u32 s87, 29
	s_barrier
	s_cbranch_scc0 .LBB0_189
	v_readlane_b32 s2, v253, 5
	v_lshl_or_b32 v140, s79, 8, v144
	v_readlane_b32 s3, v253, 6
	v_lshl_add_u32 v148, s80, 8, v142
	v_ashrrev_i32_e32 v141, 31, v140
	v_mov_b64_e32 v[138:139], s[2:3]
	v_mad_i64_i32 v[146:147], s[2:3], v148, s84, v[138:139]
	v_lshlrev_b64 v[140:141], 1, v[140:141]
	v_lshl_add_u64 v[146:147], v[146:147], 0, v[140:141]
	v_cvt_pk_bf16_f32 v124, v124, v125
	v_cvt_pk_bf16_f32 v125, v126, v127
	v_cvt_pk_bf16_f32 v126, v120, v121
	v_cvt_pk_bf16_f32 v127, v122, v123
	global_store_dwordx4 v[146:147], v[124:127], off
	v_cvt_pk_bf16_f32 v112, v112, v113
	v_cvt_pk_bf16_f32 v113, v114, v115
	v_cvt_pk_bf16_f32 v114, v104, v105
	v_or_b32_e32 v104, 16, v148
	v_mad_i64_i32 v[104:105], s[2:3], v104, s84, v[138:139]
	v_cvt_pk_bf16_f32 v115, v106, v107
	global_store_dwordx4 v[146:147], v[112:115], off offset:256
	s_and_b64 vcc, exec, s[38:39]
	s_mov_b32 s79, s40
	v_lshl_add_u64 v[112:113], v[104:105], 0, v[140:141]
	v_cvt_pk_bf16_f32 v104, v116, v117
	v_cvt_pk_bf16_f32 v105, v118, v119
	v_cvt_pk_bf16_f32 v106, v108, v109
	v_cvt_pk_bf16_f32 v107, v110, v111
	global_store_dwordx4 v[112:113], v[104:107], off
	v_cvt_pk_bf16_f32 v96, v96, v97
	v_cvt_pk_bf16_f32 v97, v98, v99
	v_cvt_pk_bf16_f32 v98, v88, v89
	v_or_b32_e32 v88, 32, v148
	v_mad_i64_i32 v[88:89], s[2:3], v88, s84, v[138:139]
	v_cvt_pk_bf16_f32 v99, v90, v91
	global_store_dwordx4 v[112:113], v[96:99], off offset:256
	s_mov_b32 s80, s42
	s_mov_b64 s[70:71], s[46:47]
	v_lshl_add_u64 v[96:97], v[88:89], 0, v[140:141]
	v_cvt_pk_bf16_f32 v88, v100, v101
	v_cvt_pk_bf16_f32 v89, v102, v103
	v_cvt_pk_bf16_f32 v90, v92, v93
	v_cvt_pk_bf16_f32 v91, v94, v95
	global_store_dwordx4 v[96:97], v[88:91], off
	v_cvt_pk_bf16_f32 v80, v80, v81
	v_cvt_pk_bf16_f32 v81, v82, v83
	v_cvt_pk_bf16_f32 v82, v72, v73
	v_or_b32_e32 v72, 48, v148
	v_mad_i64_i32 v[72:73], s[2:3], v72, s84, v[138:139]
	v_cvt_pk_bf16_f32 v83, v74, v75
	global_store_dwordx4 v[96:97], v[80:83], off offset:256
	s_mov_b64 s[68:69], s[44:45]
	s_nop 0
	v_lshl_add_u64 v[80:81], v[72:73], 0, v[140:141]
	v_cvt_pk_bf16_f32 v72, v84, v85
	v_cvt_pk_bf16_f32 v73, v86, v87
	v_cvt_pk_bf16_f32 v74, v76, v77
	v_cvt_pk_bf16_f32 v75, v78, v79
	global_store_dwordx4 v[80:81], v[72:75], off
	v_cvt_pk_bf16_f32 v68, v68, v69
	v_cvt_pk_bf16_f32 v69, v70, v71
	v_cvt_pk_bf16_f32 v70, v64, v65
	v_add_u32_e32 v64, 0x80, v148
	v_mad_i64_i32 v[64:65], s[2:3], v64, s84, v[138:139]
	v_lshl_add_u64 v[64:65], v[64:65], 0, v[140:141]
	v_cvt_pk_bf16_f32 v71, v66, v67
	global_store_dwordx4 v[80:81], v[68:71], off offset:256
	v_cvt_pk_bf16_f32 v60, v60, v61
	v_cvt_pk_bf16_f32 v61, v62, v63
	v_cvt_pk_bf16_f32 v62, v56, v57
	v_cvt_pk_bf16_f32 v63, v58, v59
	global_store_dwordx4 v[64:65], v[60:63], off
	v_cvt_pk_bf16_f32 v48, v48, v49
	v_cvt_pk_bf16_f32 v49, v50, v51
	v_cvt_pk_bf16_f32 v50, v40, v41
	v_add_u32_e32 v40, 0x90, v148
	v_mad_i64_i32 v[40:41], s[2:3], v40, s84, v[138:139]
	v_cvt_pk_bf16_f32 v51, v42, v43
	global_store_dwordx4 v[64:65], v[48:51], off offset:256
	s_nop 1
	v_lshl_add_u64 v[48:49], v[40:41], 0, v[140:141]
	v_cvt_pk_bf16_f32 v40, v52, v53
	v_cvt_pk_bf16_f32 v41, v54, v55
	v_cvt_pk_bf16_f32 v42, v44, v45
	v_cvt_pk_bf16_f32 v43, v46, v47
	global_store_dwordx4 v[48:49], v[40:43], off
	v_cvt_pk_bf16_f32 v32, v32, v33
	v_cvt_pk_bf16_f32 v33, v34, v35
	v_cvt_pk_bf16_f32 v34, v24, v25
	v_add_u32_e32 v24, 0xa0, v148
	v_mad_i64_i32 v[24:25], s[2:3], v24, s84, v[138:139]
	v_cvt_pk_bf16_f32 v35, v26, v27
	global_store_dwordx4 v[48:49], v[32:35], off offset:256
	s_nop 1
	v_lshl_add_u64 v[32:33], v[24:25], 0, v[140:141]
	v_cvt_pk_bf16_f32 v24, v36, v37
	v_cvt_pk_bf16_f32 v25, v38, v39
	v_cvt_pk_bf16_f32 v26, v28, v29
	v_cvt_pk_bf16_f32 v27, v30, v31
	global_store_dwordx4 v[32:33], v[24:27], off
	v_cvt_pk_bf16_f32 v16, v16, v17
	v_cvt_pk_bf16_f32 v17, v18, v19
	v_cvt_pk_bf16_f32 v18, v8, v9
	v_add_u32_e32 v8, 0xb0, v148
	v_mad_i64_i32 v[8:9], s[2:3], v8, s84, v[138:139]
	v_cvt_pk_bf16_f32 v19, v10, v11
	global_store_dwordx4 v[32:33], v[16:19], off offset:256
	s_nop 1
	v_lshl_add_u64 v[16:17], v[8:9], 0, v[140:141]
	v_cvt_pk_bf16_f32 v8, v20, v21
	v_cvt_pk_bf16_f32 v9, v22, v23
	v_cvt_pk_bf16_f32 v10, v12, v13
	v_cvt_pk_bf16_f32 v11, v14, v15
	global_store_dwordx4 v[16:17], v[8:11], off
	v_cvt_pk_bf16_f32 v4, v4, v5
	v_cvt_pk_bf16_f32 v5, v6, v7
	v_cvt_pk_bf16_f32 v6, v0, v1
	v_cvt_pk_bf16_f32 v7, v2, v3
	global_store_dwordx4 v[16:17], v[4:7], off offset:256
	s_cbranch_vccz .LBB0_186
	s_waitcnt vmcnt(0)
	s_cmpk_gt_u32 s34, 0xff
	s_cbranch_scc1 .LBB0_193
	s_barrier
